# k=2 rebalance: chunk workgroups take rows [0,4096) of the row passes (was [0,2048))
# baseline (speedup 1.0000x reference)
; __global__ void __launch_bounds__(512, 2) mega_fwd(Args a_) {
;     ...
;             case 2: if constexpr (PH_ON(2)) {
;                 for (int u = ti.bid; u < Mr / 128; u += ti.nblk) gmlp_unit(ti, a, l, u, lds);
;                 qk_rows(a, l, gw, ngw, lane);
;                 lora_in_rows(a, l, gw, ngw, lane);
.LBB0_449:
	s_movk_i32 s99, 0x4800
	s_sub_i32 s3, s0, s10
	s_cmp_lt_i32 s3, 64
	s_cbranch_scc1 .Lrows_default
	s_cmp_lt_i32 s2, s10
	s_cbranch_scc1 .Lrows_none
	s_sub_i32 s2, s2, s10
	s_mov_b32 s0, s3
	v_readlane_b32 s3, v255, 42
	s_lshl_b32 s48, s2, 3
	s_lshl_b32 s80, s0, 3
	s_nop 1
	s_add_i32 s48, s48, s3
	s_addk_i32 s48, 0x1000
	s_branch .Lrows_default
.Lrows_none:
	s_mov_b32 s0, s10
	v_readlane_b32 s3, v255, 42
	s_lshl_b32 s48, s2, 3
	s_lshl_b32 s80, s0, 3
	s_nop 1
	s_add_i32 s48, s48, s3
	s_movk_i32 s99, 0x1000
